# combo8b: combo8 with the barrier spin bound restored to 2^18 polls (as the baseline's)
# speedup vs baseline: 1.0228x; 1.0228x over previous
; __device__ __forceinline__ unsigned xb_ld(unsigned* p)              { return __hip_atomic_load(p, __ATOMIC_RELAXED, __HIP_MEMORY_SCOPE_AGENT); }
; #define XB_SPIN(cond, bar) do { unsigned _sp = 0; while (cond) { __builtin_amdgcn_s_sleep(1); \
;     if ((++_sp & 255u) == 0u) { if (xb_ld(&(bar)[XB_TMO])) break; if (_sp > XB_SPIN_CAP) { atomicAdd(&(bar)[XB_TMO], 1u); break; } } } } while (0)
; __device__ __forceinline__ void xcd_barrier(const XcdBarrier& b) {
;     ...
;             else XB_SPIN(xb_ld(&bar[XB_TOPGEN]) == tg, bar);
.Lxb0_spin:
	global_load_dword v5, v161, s[16:17] sc1
	s_waitcnt vmcnt(0)
	v_readfirstlane_b32 s12, v5
	s_cmp_ge_u32 s12, s2
	s_cbranch_scc1 .Lxb0_go
	s_sleep 1
	s_add_i32 s3, s3, 1
	s_cmp_lt_u32 s3, 0x40000
	s_cbranch_scc1 .Lxb0_spin
